# plus: P2b scan batched loads with next-group prefetch; P10 loop-head waits moved to prologue; P0b gain vector hoisted
# speedup vs baseline: 1.0231x; 1.0130x over previous
; __device__ __forceinline__ unsigned pk2(float lo, float hi) { return cvtpk_(lo, hi); }
; #define INF(k) ((const float*)LDP(k))
; __device__ __forceinline__ void rms_row_to_bf16(const float* xrow, const float* gain, bf16_t* orow, int lane) {
;     const f32x4* xr = (const f32x4*)xrow + lane; const f32x4* gr = (const f32x4*)gain + lane;
;     f32x4 v[8]; float s = 0.f;
; #pragma unroll
;     for (int j = 0; j < 8; ++j) { v[j] = xr[64 * j]; s += (v[j][0] * v[j][0] + v[j][1] * v[j][1]) + (v[j][2] * v[j][2] + v[j][3] * v[j][3]); }
;     const float rstd = rsqrtf(wave_sum(s) * (1.0f / DM) + RMS_EPS);
;     u32x2* o8 = (u32x2*)orow + lane;
; #pragma unroll
;     for (int j = 0; j < 8; ++j) { const f32x4 g = gr[64 * j]; u32x2 w; w.x = pk2(v[j][0] * rstd * g[0], v[j][1] * rstd * g[1]); w.y = pk2(v[j][2] * rstd * g[2], v[j][3] * rstd * g[3]); o8[64 * j] = w; }
; __global__ void __launch_bounds__(512, 2) fwd_megakernel(Args a) {
;     ...
;         for (int m = gw; m < T; m += ngw) rms_row_to_bf16(INF(I_X) + (size_t)m * DM, INF(I_GMIXPRE), HB + (size_t)m * DM, lane);
.LBB0_20:
	s_cmpk_gt_i32 s2, 0x3fff
	v_mbcnt_lo_u32_b32 v254, -1, 0
	s_cbranch_scc1 .LBB0_23
	s_add_i32 s0, 0, 0x23c40
	v_mov_b32_e32 v1, s0
	s_add_i32 s0, 0, 0x23c58
	v_mov_b32_e32 v3, s0
	ds_read_b64 v[10:11], v1
	ds_read_b64 v[12:13], v3
	v_mbcnt_hi_u32_b32 v3, -1, v254
	v_and_b32_e32 v1, 64, v3
	v_add_u32_e32 v4, 64, v1
	v_xor_b32_e32 v1, 1, v3
	v_cmp_lt_i32_e32 vcc, v1, v4
	v_xor_b32_e32 v5, 2, v3
	s_ashr_i32 s0, s3, 31
	v_cndmask_b32_e32 v1, v3, v1, vcc
	v_cmp_lt_i32_e32 vcc, v5, v4
	s_ashr_i32 s1, s92, 31
	s_add_u32 s4, s3, s92
	v_cndmask_b32_e32 v5, v3, v5, vcc
	v_lshlrev_b32_e32 v18, 2, v5
	v_xor_b32_e32 v5, 4, v3
	v_cmp_lt_i32_e32 vcc, v5, v4
	s_addc_u32 s5, s0, s1
	s_lshl_b64 s[0:1], s[4:5], 13
	v_cndmask_b32_e32 v5, v3, v5, vcc
	v_lshlrev_b32_e32 v19, 2, v5
	v_xor_b32_e32 v5, 8, v3
	v_cmp_lt_i32_e32 vcc, v5, v4
	s_ashr_i32 s51, s50, 31
	v_mov_b32_e32 v15, s1
	v_cndmask_b32_e32 v5, v3, v5, vcc
	v_lshlrev_b32_e32 v21, 2, v5
	v_xor_b32_e32 v5, 16, v3
	v_cmp_lt_i32_e32 vcc, v5, v4
	s_lshl_b64 s[4:5], s[4:5], 12
	v_mov_b32_e32 v9, 0
	v_cndmask_b32_e32 v5, v3, v5, vcc
	v_lshlrev_b32_e32 v22, 2, v5
	v_xor_b32_e32 v5, 32, v3
	v_cmp_lt_i32_e32 vcc, v5, v4
	v_lshlrev_b32_e32 v1, 2, v1
	s_movk_i32 s3, 0x1000
	v_cndmask_b32_e32 v3, v3, v5, vcc
	v_lshlrev_b32_e32 v23, 2, v3
	v_lshl_or_b32 v3, v2, 4, s0
	s_lshl_b64 s[0:1], s[50:51], 13
	s_add_u32 s4, s52, s4
	s_addc_u32 s5, s53, s5
	v_lshl_add_u64 v[4:5], s[4:5], 0, v[8:9]
	s_mov_b64 s[4:5], 0x5c00800
	v_or_b32_e32 v14, 0x1000, v3
	v_lshl_add_u64 v[16:17], v[4:5], 0, s[4:5]
	s_lshl_b64 s[4:5], s[50:51], 12
	v_lshlrev_b32_e32 v8, 4, v2
	v_mov_b32_e32 v24, 0x358637bd
	s_mov_b32 s8, 0x800000
	s_waitcnt lgkmcnt(0)
	v_readfirstlane_b32 s39, v13
	v_readfirstlane_b32 s38, v12
	v_add_u32_e32 v110, 0x1000, v8
	s_nop 3
	global_load_dwordx4 v[200:203], v8, s[38:39]
	global_load_dwordx4 v[204:207], v8, s[38:39] offset:1024
	global_load_dwordx4 v[208:211], v8, s[38:39] offset:2048
	global_load_dwordx4 v[212:215], v8, s[38:39] offset:3072
	global_load_dwordx4 v[216:219], v110, s[38:39]
	global_load_dwordx4 v[220:223], v110, s[38:39] offset:1024
	global_load_dwordx4 v[224:227], v110, s[38:39] offset:2048
	global_load_dwordx4 v[228:231], v110, s[38:39] offset:3072
; __device__ __forceinline__ unsigned pk2(float lo, float hi) { return cvtpk_(lo, hi); }
; __device__ __forceinline__ void rms_row_to_bf16(const float* xrow, const float* gain, bf16_t* orow, int lane) {
;     const f32x4* xr = (const f32x4*)xrow + lane; const f32x4* gr = (const f32x4*)gain + lane;
;     f32x4 v[8]; float s = 0.f;
; #pragma unroll
;     for (int j = 0; j < 8; ++j) { v[j] = xr[64 * j]; s += (v[j][0] * v[j][0] + v[j][1] * v[j][1]) + (v[j][2] * v[j][2] + v[j][3] * v[j][3]); }
;     const float rstd = rsqrtf(wave_sum(s) * (1.0f / DM) + RMS_EPS);
;     u32x2* o8 = (u32x2*)orow + lane;
; #pragma unroll
;     for (int j = 0; j < 8; ++j) { const f32x4 g = gr[64 * j]; u32x2 w; w.x = pk2(v[j][0] * rstd * g[0], v[j][1] * rstd * g[1]); w.y = pk2(v[j][2] * rstd * g[2], v[j][3] * rstd * g[3]); o8[64 * j] = w; }
.LBB0_22:
	s_waitcnt lgkmcnt(1)
	v_readfirstlane_b32 s7, v11
	v_readfirstlane_b32 s6, v10
	s_add_i32 s2, s2, s50
	s_cmpk_gt_i32 s2, 0x3fff
	v_lshl_add_u64 v[54:55], s[6:7], 0, v[14:15]
	global_load_dwordx4 v[26:29], v[54:55], off offset:-4096
	global_load_dwordx4 v[30:33], v[54:55], off offset:-3072
	global_load_dwordx4 v[34:37], v[54:55], off offset:-2048
	global_load_dwordx4 v[38:41], v[54:55], off offset:1024
	global_load_dwordx4 v[42:45], v[54:55], off
	global_load_dwordx4 v[46:49], v[54:55], off offset:-1024
	global_load_dwordx4 v[50:53], v[54:55], off offset:2048
	global_load_dwordx4 v[2:5], v[54:55], off offset:3072
	s_waitcnt lgkmcnt(0)
	v_readfirstlane_b32 s7, v13
	v_readfirstlane_b32 s6, v12
	v_lshl_add_u64 v[14:15], v[14:15], 0, s[0:1]
	s_waitcnt vmcnt(7)
	v_mov_b32_e32 v60, v27
	s_nop 1
	s_waitcnt vmcnt(6)
	v_mov_b32_e32 v61, v31
	s_waitcnt vmcnt(5)
	v_pk_mul_f32 v[62:63], v[36:37], v[36:37]
	v_pk_mul_f32 v[64:65], v[34:35], v[34:35]
	s_waitcnt vmcnt(4)
	v_pk_mul_f32 v[66:67], v[40:41], v[40:41]
	v_pk_mul_f32 v[68:69], v[38:39], v[38:39]
	v_mov_b32_e32 v72, v29
	v_mov_b32_e32 v73, v33
	v_mov_b32_e32 v58, v26
	v_mov_b32_e32 v59, v30
	v_mov_b32_e32 v70, v28
	v_mov_b32_e32 v71, v32
	v_pk_mov_b32 v[82:83], v[64:65], v[62:63] op_sel:[1,0]
	v_mov_b32_e32 v65, v63
	v_pk_mov_b32 v[62:63], v[68:69], v[66:67] op_sel:[1,0]
	v_mov_b32_e32 v69, v67
	v_pk_mul_f32 v[60:61], v[60:61], v[60:61]
	v_pk_mul_f32 v[66:67], v[72:73], v[72:73]
	v_pk_fma_f32 v[58:59], v[58:59], v[58:59], v[60:61]
	v_pk_fma_f32 v[60:61], v[70:71], v[70:71], v[66:67]
	s_waitcnt vmcnt(2)
	v_mul_f32_e32 v74, v47, v47
	v_mul_f32_e32 v76, v49, v49
	v_pk_add_f32 v[64:65], v[82:83], v[64:65]
	v_pk_add_f32 v[58:59], v[58:59], v[60:61]
	v_mul_f32_e32 v25, v42, v42
	v_mul_f32_e32 v81, v43, v43
	v_mul_f32_e32 v84, v44, v44
	v_mul_f32_e32 v85, v45, v45
	v_pk_fma_f32 v[72:73], v[46:47], v[46:47], v[74:75] op_sel_hi:[1,1,0]
	v_pk_fma_f32 v[74:75], v[48:49], v[48:49], v[76:77] op_sel_hi:[1,1,0]
	v_pk_add_f32 v[64:65], v[64:65], v[64:65] op_sel:[0,1] op_sel_hi:[1,0]
	v_pk_add_f32 v[58:59], v[58:59], v[58:59] op_sel:[0,1] op_sel_hi:[1,0]
	v_mov_b32_e32 v73, v84
	v_mov_b32_e32 v75, v85
	v_mov_b32_e32 v65, v81
	v_mov_b32_e32 v59, v25
	v_pk_add_f32 v[60:61], v[72:73], v[74:75]
	v_pk_add_f32 v[58:59], v[58:59], v[64:65]
	s_waitcnt vmcnt(1)
	v_mul_f32_e32 v78, v51, v51
	v_mul_f32_e32 v80, v53, v53
	v_pk_add_f32 v[62:63], v[62:63], v[68:69]
	v_pk_add_f32 v[58:59], v[58:59], v[60:61]
	s_waitcnt vmcnt(0)
	v_mul_f32_e32 v86, v4, v4
	v_mul_f32_e32 v87, v5, v5
	v_mul_f32_e32 v88, v2, v2
	v_mul_f32_e32 v89, v3, v3
	v_pk_fma_f32 v[76:77], v[50:51], v[50:51], v[78:79] op_sel_hi:[1,1,0]
	v_pk_fma_f32 v[78:79], v[52:53], v[52:53], v[80:81] op_sel_hi:[1,1,0]
	v_pk_add_f32 v[62:63], v[62:63], v[62:63] op_sel:[0,1] op_sel_hi:[1,0]
	v_pk_add_f32 v[58:59], v[58:59], v[58:59] op_sel:[0,1] op_sel_hi:[1,0]
	v_mov_b32_e32 v77, v86
	v_mov_b32_e32 v79, v87
	v_mov_b32_e32 v63, v89
	v_mov_b32_e32 v59, v88
	v_pk_add_f32 v[66:67], v[76:77], v[78:79]
	v_pk_add_f32 v[58:59], v[58:59], v[62:63]
	s_nop 0
	v_pk_add_f32 v[58:59], v[58:59], v[66:67]
	s_nop 0
	v_add_f32_e32 v25, v58, v59
	ds_bpermute_b32 v58, v1, v25
	s_waitcnt lgkmcnt(0)
	v_add_f32_e32 v25, v25, v58
	ds_bpermute_b32 v58, v18, v25
	s_waitcnt lgkmcnt(0)
	v_add_f32_e32 v25, v25, v58
	ds_bpermute_b32 v58, v19, v25
	s_waitcnt lgkmcnt(0)
	v_add_f32_e32 v25, v25, v58
	ds_bpermute_b32 v58, v21, v25
	s_waitcnt lgkmcnt(0)
	v_add_f32_e32 v25, v25, v58
	ds_bpermute_b32 v58, v22, v25
	s_waitcnt lgkmcnt(0)
	v_add_f32_e32 v25, v25, v58
	ds_bpermute_b32 v58, v23, v25
	s_waitcnt lgkmcnt(0)
	v_add_f32_e32 v25, v25, v58
	v_fmamk_f32 v25, v25, 0x3a000000, v24
	v_mul_f32_e32 v58, 0x4b800000, v25
	v_cmp_gt_f32_e32 vcc, s8, v25
	s_nop 1
	v_cndmask_b32_e32 v25, v25, v58, vcc
	v_rsq_f32_e32 v25, v25
	s_nop 0
	v_mul_f32_e32 v58, 0x45800000, v25
	v_cndmask_b32_e32 v58, v25, v58, vcc
	v_pk_mul_f32 v[26:27], v[26:27], v[58:59] op_sel_hi:[1,0]
	v_pk_mul_f32 v[28:29], v[28:29], v[58:59] op_sel_hi:[1,0]
	v_pk_mul_f32 v[26:27], v[200:201], v[26:27]
	v_pk_mul_f32 v[28:29], v[202:203], v[28:29]
	v_cvt_pk_bf16_f32 v26, v26, v27
	v_cvt_pk_bf16_f32 v27, v28, v29
	global_store_dwordx2 v[16:17], v[26:27], off offset:-2048
	v_pk_mul_f32 v[30:31], v[30:31], v[58:59] op_sel_hi:[1,0]
	v_pk_mul_f32 v[32:33], v[32:33], v[58:59] op_sel_hi:[1,0]
	v_pk_mul_f32 v[2:3], v[2:3], v[58:59] op_sel_hi:[1,0]
	v_pk_mul_f32 v[4:5], v[4:5], v[58:59] op_sel_hi:[1,0]
	v_pk_mul_f32 v[26:27], v[204:205], v[30:31]
	v_pk_mul_f32 v[28:29], v[206:207], v[32:33]
	v_cvt_pk_bf16_f32 v26, v26, v27
	v_cvt_pk_bf16_f32 v27, v28, v29
	global_store_dwordx2 v[16:17], v[26:27], off offset:-1536
	v_pk_mul_f32 v[30:31], v[34:35], v[58:59] op_sel_hi:[1,0]
	v_pk_mul_f32 v[32:33], v[36:37], v[58:59] op_sel_hi:[1,0]
	v_pk_mul_f32 v[34:35], v[48:49], v[58:59] op_sel_hi:[1,0]
	v_pk_mul_f32 v[26:27], v[208:209], v[30:31]
	v_pk_mul_f32 v[28:29], v[210:211], v[32:33]
	v_cvt_pk_bf16_f32 v26, v26, v27
	v_cvt_pk_bf16_f32 v27, v28, v29
	global_store_dwordx2 v[16:17], v[26:27], off offset:-1024
	v_pk_mul_f32 v[32:33], v[46:47], v[58:59] op_sel_hi:[1,0]
	v_lshl_add_u64 v[30:31], s[6:7], 0, v[8:9]
	v_add_co_u32_e32 v30, vcc, s3, v30
	v_pk_mul_f32 v[26:27], v[212:213], v[32:33]
	v_pk_mul_f32 v[28:29], v[214:215], v[34:35]
	v_cvt_pk_bf16_f32 v26, v26, v27
	v_cvt_pk_bf16_f32 v27, v28, v29
	v_addc_co_u32_e32 v31, vcc, 0, v31, vcc
	global_store_dwordx2 v[16:17], v[26:27], off offset:-512
	v_pk_mul_f32 v[32:33], v[42:43], v[58:59] op_sel_hi:[1,0]
	v_pk_mul_f32 v[34:35], v[44:45], v[58:59] op_sel_hi:[1,0]
	v_pk_mul_f32 v[26:27], v[216:217], v[32:33]
	v_pk_mul_f32 v[28:29], v[218:219], v[34:35]
	v_cvt_pk_bf16_f32 v26, v26, v27
	v_cvt_pk_bf16_f32 v27, v28, v29
	global_store_dwordx2 v[16:17], v[26:27], off
	v_pk_mul_f32 v[32:33], v[38:39], v[58:59] op_sel_hi:[1,0]
	v_pk_mul_f32 v[34:35], v[40:41], v[58:59] op_sel_hi:[1,0]
	v_pk_mul_f32 v[26:27], v[32:33], v[220:221]
	v_pk_mul_f32 v[28:29], v[34:35], v[222:223]
	v_cvt_pk_bf16_f32 v26, v26, v27
	v_cvt_pk_bf16_f32 v27, v28, v29
	global_store_dwordx2 v[16:17], v[26:27], off offset:512
	v_pk_mul_f32 v[32:33], v[50:51], v[58:59] op_sel_hi:[1,0]
	v_pk_mul_f32 v[34:35], v[52:53], v[58:59] op_sel_hi:[1,0]
	v_pk_mul_f32 v[26:27], v[32:33], v[224:225]
	v_pk_mul_f32 v[28:29], v[34:35], v[226:227]
	v_cvt_pk_bf16_f32 v26, v26, v27
	v_cvt_pk_bf16_f32 v27, v28, v29
	global_store_dwordx2 v[16:17], v[26:27], off offset:1024
	v_pk_mul_f32 v[2:3], v[2:3], v[228:229]
	v_pk_mul_f32 v[4:5], v[4:5], v[230:231]
	v_cvt_pk_bf16_f32 v2, v2, v3
	v_cvt_pk_bf16_f32 v3, v4, v5
	global_store_dwordx2 v[16:17], v[2:3], off offset:1536
	v_lshl_add_u64 v[16:17], v[16:17], 0, s[4:5]
	s_cbranch_scc0 .LBB0_22

; __device__ __forceinline__ unsigned pk2(float lo, float hi) { return cvtpk_(lo, hi); }
; __global__ void __launch_bounds__(512, 2) fwd_megakernel(Args a) {
;     ...
;         for (int item = gt; item < 16 * 128 * 64; item += ngt) {
;             const int kp = item & 63, dv = (item >> 6) & 127, bh = item >> 13;
;             f32x2 s = {0.f, 0.f};
;             const unsigned* up = (const unsigned*)(U + (size_t)bh * 128 * 16384 + (size_t)dv * 128) + kp;
;             const f32x2* dp = (const f32x2*)(DC + (size_t)bh * 128 * 128) + kp;
;             unsigned* sp = (unsigned*)(STb + (size_t)bh * 128 * 16384 + (size_t)dv * 128) + kp;
; #pragma unroll 8
;             for (int c = 0; c < 128; ++c) {
;                 sp[(size_t)c * 8192] = pk2(s[0], s[1]);
;                 const unsigned ub = up[(size_t)c * 8192]; const f32x2 u = {bflo(ub), bfhi(ub)}, d = dp[(size_t)c * 64];
;                 s = d * s + u;
;             }
.LBB0_291:
	s_mov_b64 s[24:25], 0x8000
	s_mov_b64 s[26:27], 0xa800000
	v_lshl_add_u64 v[82:83], v[12:13], 0, s[26:27]
	v_lshl_add_u64 v[80:81], v[10:11], 0, s[8:9]
	global_load_dword v32, v[80:81], off
	global_load_dwordx2 v[40:41], v[8:9], off offset:-3584
	v_lshl_add_u64 v[80:81], v[80:81], 0, s[24:25]
	global_load_dword v33, v[80:81], off
	global_load_dwordx2 v[42:43], v[8:9], off offset:-3072
	v_lshl_add_u64 v[80:81], v[80:81], 0, s[24:25]
	global_load_dword v34, v[80:81], off
	global_load_dwordx2 v[44:45], v[8:9], off offset:-2560
	v_lshl_add_u64 v[80:81], v[80:81], 0, s[24:25]
	global_load_dword v35, v[80:81], off
	global_load_dwordx2 v[46:47], v[8:9], off offset:-2048
	v_lshl_add_u64 v[80:81], v[80:81], 0, s[24:25]
	global_load_dword v36, v[80:81], off
	global_load_dwordx2 v[48:49], v[8:9], off offset:-1536
	v_lshl_add_u64 v[80:81], v[80:81], 0, s[24:25]
	global_load_dword v37, v[80:81], off
	global_load_dwordx2 v[50:51], v[8:9], off offset:-1024
	v_lshl_add_u64 v[80:81], v[80:81], 0, s[24:25]
	global_load_dword v38, v[80:81], off
	global_load_dwordx2 v[52:53], v[8:9], off offset:-512
	v_lshl_add_u64 v[80:81], v[80:81], 0, s[24:25]
	global_load_dword v39, v[80:81], off
	global_load_dwordx2 v[54:55], v[8:9], off
	s_waitcnt vmcnt(0)
.Lscan_loop:
	s_add_u32 s8, s8, 0x40000
	s_addc_u32 s9, s9, 0
	v_lshl_add_u64 v[8:9], v[8:9], 0, s[6:7]
	v_lshl_add_u64 v[80:81], v[10:11], 0, s[8:9]
	global_load_dword v56, v[80:81], off
	global_load_dwordx2 v[64:65], v[8:9], off offset:-3584
	v_lshl_add_u64 v[80:81], v[80:81], 0, s[24:25]
	global_load_dword v57, v[80:81], off
	global_load_dwordx2 v[66:67], v[8:9], off offset:-3072
	v_lshl_add_u64 v[80:81], v[80:81], 0, s[24:25]
	global_load_dword v58, v[80:81], off
	global_load_dwordx2 v[68:69], v[8:9], off offset:-2560
	v_lshl_add_u64 v[80:81], v[80:81], 0, s[24:25]
	global_load_dword v59, v[80:81], off
	global_load_dwordx2 v[70:71], v[8:9], off offset:-2048
	v_lshl_add_u64 v[80:81], v[80:81], 0, s[24:25]
	global_load_dword v60, v[80:81], off
	global_load_dwordx2 v[72:73], v[8:9], off offset:-1536
	v_lshl_add_u64 v[80:81], v[80:81], 0, s[24:25]
	global_load_dword v61, v[80:81], off
	global_load_dwordx2 v[74:75], v[8:9], off offset:-1024
	v_lshl_add_u64 v[80:81], v[80:81], 0, s[24:25]
	global_load_dword v62, v[80:81], off
	global_load_dwordx2 v[76:77], v[8:9], off offset:-512
	v_lshl_add_u64 v[80:81], v[80:81], 0, s[24:25]
	global_load_dword v63, v[80:81], off
	global_load_dwordx2 v[78:79], v[8:9], off
	v_cvt_pk_bf16_f32 v84, v14, v15
	v_lshlrev_b32_e32 v28, 16, v32
	v_and_b32_e32 v29, 0xffff0000, v32
	global_store_dword v[82:83], v84, off
	v_lshl_add_u64 v[82:83], v[82:83], 0, s[24:25]
	v_pk_fma_f32 v[14:15], v[14:15], v[40:41], v[28:29]
	s_nop 0
	v_cvt_pk_bf16_f32 v85, v14, v15
	v_lshlrev_b32_e32 v28, 16, v33
	v_and_b32_e32 v29, 0xffff0000, v33
	global_store_dword v[82:83], v85, off
	v_lshl_add_u64 v[82:83], v[82:83], 0, s[24:25]
	v_pk_fma_f32 v[14:15], v[14:15], v[42:43], v[28:29]
	s_nop 0
	v_cvt_pk_bf16_f32 v86, v14, v15
	v_lshlrev_b32_e32 v28, 16, v34
	v_and_b32_e32 v29, 0xffff0000, v34
	global_store_dword v[82:83], v86, off
	v_lshl_add_u64 v[82:83], v[82:83], 0, s[24:25]
	v_pk_fma_f32 v[14:15], v[14:15], v[44:45], v[28:29]
	s_nop 0
	v_cvt_pk_bf16_f32 v87, v14, v15
	v_lshlrev_b32_e32 v28, 16, v35
	v_and_b32_e32 v29, 0xffff0000, v35
	global_store_dword v[82:83], v87, off
	v_lshl_add_u64 v[82:83], v[82:83], 0, s[24:25]
	v_pk_fma_f32 v[14:15], v[14:15], v[46:47], v[28:29]
	s_nop 0
	v_cvt_pk_bf16_f32 v88, v14, v15
	v_lshlrev_b32_e32 v28, 16, v36
	v_and_b32_e32 v29, 0xffff0000, v36
	global_store_dword v[82:83], v88, off
	v_lshl_add_u64 v[82:83], v[82:83], 0, s[24:25]
	v_pk_fma_f32 v[14:15], v[14:15], v[48:49], v[28:29]
	s_nop 0
	v_cvt_pk_bf16_f32 v89, v14, v15
	v_lshlrev_b32_e32 v28, 16, v37
	v_and_b32_e32 v29, 0xffff0000, v37
	global_store_dword v[82:83], v89, off
	v_lshl_add_u64 v[82:83], v[82:83], 0, s[24:25]
	v_pk_fma_f32 v[14:15], v[14:15], v[50:51], v[28:29]
	s_nop 0
	v_cvt_pk_bf16_f32 v90, v14, v15
	v_lshlrev_b32_e32 v28, 16, v38
	v_and_b32_e32 v29, 0xffff0000, v38
	global_store_dword v[82:83], v90, off
	v_lshl_add_u64 v[82:83], v[82:83], 0, s[24:25]
	v_pk_fma_f32 v[14:15], v[14:15], v[52:53], v[28:29]
	s_nop 0
	v_cvt_pk_bf16_f32 v91, v14, v15
	v_lshlrev_b32_e32 v28, 16, v39
	v_and_b32_e32 v29, 0xffff0000, v39
	global_store_dword v[82:83], v91, off
	v_lshl_add_u64 v[82:83], v[82:83], 0, s[24:25]
	v_pk_fma_f32 v[14:15], v[14:15], v[54:55], v[28:29]
	s_nop 0
	s_waitcnt vmcnt(8)
	v_mov_b32_e32 v32, v56
	v_mov_b32_e32 v33, v57
	v_mov_b32_e32 v34, v58
	v_mov_b32_e32 v35, v59
	v_mov_b32_e32 v36, v60
	v_mov_b32_e32 v37, v61
	v_mov_b32_e32 v38, v62
	v_mov_b32_e32 v39, v63
	v_mov_b64_e32 v[40:41], v[64:65]
	v_mov_b64_e32 v[42:43], v[66:67]
	v_mov_b64_e32 v[44:45], v[68:69]
	v_mov_b64_e32 v[46:47], v[70:71]
	v_mov_b64_e32 v[48:49], v[72:73]
	v_mov_b64_e32 v[50:51], v[74:75]
	v_mov_b64_e32 v[52:53], v[76:77]
	v_mov_b64_e32 v[54:55], v[78:79]
	s_cmp_eq_u32 s8, 0x400000
	s_cbranch_scc0 .Lscan_loop
	v_add_u32_e32 v16, s74, v16
	v_cmp_lt_i32_e32 vcc, s22, v16
	s_or_b64 s[4:5], vcc, s[4:5]
	v_add_u32_e32 v17, s10, v17
	s_andn2_b64 exec, exec, s[4:5]
	s_cbranch_execnz .LBB0_290

; template <bool XIB, bool XOB> __device__ __forceinline__ void rowpass(const bf16_t* Y, const float* part, const void* Xin, void* Xout, const float* g_post, const float* g_pre, bf16_t* Hout, int gw, int ngw, int lane_) {
;     int lane = lane_; asm volatile("" : "+v"(lane));
;     f32x4 gp[8];
; #pragma unroll
;     for (int j = 0; j < 8; ++j) gp[j] = ((const f32x4*)g_post)[lane + 64 * j];
;     u32x2 ny[8]; f32x4 nxf[8]; u32x2 nxb[8]; float np = 0.f;
;     ...
;     int row = gw;
;     if (row < T) RP_LOAD(row);
;     for (; row < T; row += ngw) {
;         u32x2 cy[8]; f32x4 cx[8]; float p = np;
; #pragma unroll
;         for (int j = 0; j < 8; ++j) { cy[j] = ny[j]; if (XIB) cx[j] = (f32x4){bflo(nxb[j].x), bfhi(nxb[j].x), bflo(nxb[j].y), bfhi(nxb[j].y)}; else cx[j] = nxf[j]; }
;         if (row + ngw < T) RP_LOAD(row + ngw);
.LBB0_1085:
	s_or_b64 exec, exec, s[0:1]
	s_waitcnt lgkmcnt(0)
	s_barrier
	v_mbcnt_lo_u32_b32 v0, -1, 0
	v_mbcnt_hi_u32_b32 v0, -1, v0
	s_add_i32 s0, 0, 0x23cd8
	v_add_u32_e32 v4, s84, v0
	v_mov_b32_e32 v0, s0
	ds_read2_b64 v[0:3], v0 offset1:1
	v_readfirstlane_b32 s0, v4
	s_ashr_i32 s0, s0, 6
	s_add_i32 s0, s0, s92
	v_and_b32_e32 v32, 63, v4
	s_waitcnt lgkmcnt(0)
	v_readfirstlane_b32 s4, v3
	v_readfirstlane_b32 s5, v2
	v_readfirstlane_b32 s3, v1
	v_readfirstlane_b32 s2, v0
	s_cmpk_lt_i32 s0, 0x4000
	s_cbranch_scc0 .LBB0_1090
	v_ashrrev_i32_e32 v33, 31, v32
	v_lshlrev_b64 v[34:35], 4, v[32:33]
	v_lshl_add_u64 v[16:17], s[2:3], 0, v[34:35]
	v_add_co_u32_e32 v36, vcc, 0x1000, v16
	s_ashr_i32 s1, s0, 31
	s_nop 0
	v_addc_co_u32_e32 v37, vcc, 0, v17, vcc
	s_lshl_b64 s[2:3], s[0:1], 7
	global_load_dwordx4 v[0:3], v[16:17], off
	global_load_dwordx4 v[4:7], v[16:17], off offset:1024
	global_load_dwordx4 v[8:11], v[16:17], off offset:2048
	global_load_dwordx4 v[12:15], v[16:17], off offset:3072
	s_nop 0
	global_load_dwordx4 v[16:19], v[36:37], off
	global_load_dwordx4 v[20:23], v[36:37], off offset:1024
	global_load_dwordx4 v[24:27], v[36:37], off offset:2048
	global_load_dwordx4 v[28:31], v[36:37], off offset:3072
	s_add_u32 s2, s10, s2
	v_lshlrev_b32_e32 v36, 2, v32
	s_addc_u32 s3, s11, s3
	v_and_b32_e32 v50, 0x7c, v36
	global_load_dword v109, v50, s[2:3]
	s_lshl_b64 s[2:3], s[0:1], 12
	s_add_u32 s6, s56, s2
	s_addc_u32 s7, s57, s3
	s_add_u32 s2, s52, s2
	v_lshlrev_b64 v[40:41], 3, v[32:33]
	s_addc_u32 s3, s53, s3
	v_lshl_add_u64 v[32:33], s[2:3], 0, v[40:41]
	s_mov_b64 s[2:3], 0x18e00000
	v_lshl_add_u64 v[44:45], v[32:33], 0, s[2:3]
	s_mov_b32 s2, 0x18e00000
	v_lshl_add_u64 v[38:39], s[6:7], 0, v[40:41]
	v_add_co_u32_e32 v46, vcc, s2, v32
	s_lshl_b64 s[2:3], s[0:1], 13
	s_nop 0
	v_addc_co_u32_e32 v47, vcc, 0, v33, vcc
	global_load_dwordx2 v[68:69], v[38:39], off
	global_load_dwordx2 v[66:67], v[38:39], off offset:512
	global_load_dwordx2 v[64:65], v[38:39], off offset:1024
	global_load_dwordx2 v[60:61], v[38:39], off offset:1536
	global_load_dwordx2 v[98:99], v[44:45], off offset:512
	global_load_dwordx2 v[96:97], v[44:45], off offset:1024
	global_load_dwordx2 v[92:93], v[44:45], off offset:1536
	global_load_dwordx2 v[88:89], v[44:45], off offset:2048
	global_load_dwordx2 v[48:49], v[38:39], off offset:2048
	global_load_dwordx2 v[42:43], v[38:39], off offset:2560
	global_load_dwordx2 v[36:37], v[38:39], off offset:3072
	global_load_dwordx2 v[32:33], v[38:39], off offset:3584
	global_load_dwordx2 v[100:101], v[46:47], off
	global_load_dwordx2 v[94:95], v[44:45], off offset:2560
	global_load_dwordx2 v[90:91], v[44:45], off offset:3072
	global_load_dwordx2 v[86:87], v[44:45], off offset:3584
	v_mbcnt_hi_u32_b32 v38, -1, v254
	v_and_b32_e32 v39, 64, v38
	v_add_u32_e32 v39, 64, v39
	v_xor_b32_e32 v44, 1, v38
	v_cmp_lt_i32_e32 vcc, v44, v39
	s_add_u32 s2, s5, s2
	s_addc_u32 s3, s4, s3
	v_cndmask_b32_e32 v44, v38, v44, vcc
	v_lshlrev_b32_e32 v102, 2, v44
	v_xor_b32_e32 v44, 2, v38
	v_cmp_lt_i32_e32 vcc, v44, v39
	s_add_i32 s6, s0, s50
	s_ashr_i32 s7, s6, 31
	v_cndmask_b32_e32 v44, v38, v44, vcc
	v_lshlrev_b32_e32 v103, 2, v44
	v_xor_b32_e32 v44, 4, v38
	v_cmp_lt_i32_e32 vcc, v44, v39
	s_lshl_b64 s[4:5], s[6:7], 7
	v_lshl_add_u64 v[34:35], s[2:3], 0, v[34:35]
	v_cndmask_b32_e32 v44, v38, v44, vcc
	v_lshlrev_b32_e32 v104, 2, v44
	v_xor_b32_e32 v44, 8, v38
	v_cmp_lt_i32_e32 vcc, v44, v39
	s_mov_b64 s[2:3], 0x1000
	s_ashr_i32 s51, s50, 31
	v_cndmask_b32_e32 v44, v38, v44, vcc
	v_lshlrev_b32_e32 v105, 2, v44
	v_xor_b32_e32 v44, 16, v38
	v_cmp_lt_i32_e32 vcc, v44, v39
	v_mov_b32_e32 v39, s5
	s_lshl_b64 s[6:7], s[6:7], 12
	v_cndmask_b32_e32 v38, v38, v44, vcc
	v_lshlrev_b32_e32 v106, 2, v38
	v_or_b32_e32 v38, s4, v50
	s_mov_b64 s[4:5], 0xa600000
	v_lshl_add_u64 v[34:35], v[34:35], 0, s[2:3]
	s_lshl_b64 s[2:3], s[50:51], 13
	v_lshl_add_u64 v[38:39], v[38:39], 0, s[4:5]
	s_lshl_b64 s[4:5], s[50:51], 7
	v_lshl_add_u64 v[40:41], s[6:7], 0, v[40:41]
	s_lshl_b64 s[6:7], s[50:51], 12
	v_mov_b32_e32 v107, 0x358637bd
	s_mov_b32 s1, 0x800000
	s_waitcnt vmcnt(15)
	v_mov_b64_e32 v[44:45], v[68:69]
	s_waitcnt vmcnt(14)
	v_mov_b64_e32 v[46:47], v[66:67]
	s_waitcnt vmcnt(13)
	v_mov_b64_e32 v[50:51], v[64:65]
	s_waitcnt vmcnt(12)
	v_mov_b64_e32 v[52:53], v[60:61]
	v_mov_b32_e32 v108, v109
	s_waitcnt vmcnt(7)
	v_mov_b64_e32 v[54:55], v[48:49]
	s_waitcnt vmcnt(6)
	v_mov_b64_e32 v[56:57], v[42:43]
	s_waitcnt vmcnt(5)
	v_mov_b64_e32 v[58:59], v[36:37]
	s_waitcnt vmcnt(4)
	v_mov_b64_e32 v[62:63], v[32:33]
	s_waitcnt vmcnt(0)
	s_branch .LBB0_1088

; template <bool XIB, bool XOB> __device__ __forceinline__ void rowpass(const bf16_t* Y, const float* part, const void* Xin, void* Xout, const float* g_post, const float* g_pre, bf16_t* Hout, int gw, int ngw, int lane_) {
;     ...
;     int row = gw;
;     if (row < T) RP_LOAD(row);
;     for (; row < T; row += ngw) {
;         u32x2 cy[8]; f32x4 cx[8]; float p = np;
; #pragma unroll
;         for (int j = 0; j < 8; ++j) { cy[j] = ny[j]; if (XIB) cx[j] = (f32x4){bflo(nxb[j].x), bfhi(nxb[j].x), bflo(nxb[j].y), bfhi(nxb[j].y)}; else cx[j] = nxf[j]; }
;         if (row + ngw < T) RP_LOAD(row + ngw);
.LBB0_1088:
	s_add_i32 s0, s0, s50
	s_cmpk_gt_i32 s0, 0x3fff
	s_cselect_b64 s[8:9], -1, 0
	s_and_b64 vcc, exec, s[8:9]
	v_mov_b32_e32 v78, v100
	v_mov_b32_e32 v79, v101
	v_mov_b32_e32 v80, v98
	v_mov_b32_e32 v81, v99
	v_mov_b32_e32 v82, v96
	v_mov_b32_e32 v83, v97
	v_mov_b32_e32 v70, v92
	v_mov_b32_e32 v71, v93
	v_mov_b32_e32 v72, v88
	v_mov_b32_e32 v73, v89
	v_mov_b32_e32 v74, v94
	v_mov_b32_e32 v75, v95
	v_mov_b32_e32 v76, v90
	v_mov_b32_e32 v77, v91
	v_mov_b32_e32 v84, v86
	v_mov_b32_e32 v85, v87
	s_cbranch_vccnz .LBB0_1087
	v_lshl_add_u64 v[44:45], s[52:53], 0, v[40:41]
	v_add_co_u32_e32 v110, vcc, 0xa800000, v44
	v_lshl_add_u64 v[62:63], s[52:53], 0, v[38:39]
	s_nop 0
	v_addc_co_u32_e32 v111, vcc, 0, v45, vcc
	v_add_co_u32_e32 v112, vcc, 0x18e00000, v44
	s_nop 1
	v_addc_co_u32_e32 v113, vcc, 0, v45, vcc
	global_load_dword v108, v[62:63], off
	global_load_dwordx2 v[44:45], v[110:111], off
	global_load_dwordx2 v[46:47], v[110:111], off offset:512
	global_load_dwordx2 v[50:51], v[110:111], off offset:1024
	global_load_dwordx2 v[52:53], v[110:111], off offset:1536
	global_load_dwordx2 v[54:55], v[110:111], off offset:2048
	global_load_dwordx2 v[56:57], v[110:111], off offset:2560
	global_load_dwordx2 v[58:59], v[110:111], off offset:3072
	global_load_dwordx2 v[70:71], v[112:113], off offset:1536
	global_load_dwordx2 v[72:73], v[112:113], off offset:2048
	global_load_dwordx2 v[74:75], v[112:113], off offset:2560
	global_load_dwordx2 v[76:77], v[112:113], off offset:3072
	global_load_dwordx2 v[78:79], v[112:113], off
	global_load_dwordx2 v[80:81], v[112:113], off offset:512
	global_load_dwordx2 v[82:83], v[112:113], off offset:1024
	global_load_dwordx2 v[62:63], v[110:111], off offset:3584
	global_load_dwordx2 v[84:85], v[112:113], off offset:3584
	s_branch .LBB0_1087
